# attention: stick-breaking units rebalanced (first-half workgroups take one SB unit each, second-half three) on top of final combined
# baseline (speedup 1.0000x reference)
; #define LAS __attribute__((address_space(3)))
; __device__ __forceinline__ int lane_now() { int x; asm volatile("v_mbcnt_lo_u32_b32 %0, -1, 0\n\tv_mbcnt_hi_u32_b32 %0, -1, %0" : "=v"(x)); return x; }
; __device__ __forceinline__ void sb_unit(LAS unsigned char* lds, const bf16_t* qkv, bf16_t* attout, int b, int h, int qb, int wid, int) {
;     const int lane = lane_now(); int r32 = lane & 31, hi = lane >> 5; const Offs of0 = make_offs(wid, lane); const unsigned offK = of0.k[0] * 2u, offV = of0.v[0] * 2u;
;     const int ldsbase = (int)(unsigned)(unsigned long)lds;
;     const bf16_t* base = qkv + (size_t)b * SEQ * LDQ; const bf16_t* Kp = base + 1024 + h * 128; const bf16_t* Vp = base + 2048 + h * 128;
;     const int q0 = qb * 256 + wid * 32;
;     bf16x8 qr[8]; { const bf16_t* Qw = base + (size_t)(q0 + r32) * LDQ + h * 128 + hi * 8;
; #pragma unroll
;         for (int d0 = 0; d0 < 8; ++d0) qr[d0] = *(const bf16x8*)(Qw + d0 * 16); }
;     f32x16 o[4] = {}; float Rp = 1.0f;
;     const int jmax = qb * 4 + 3, nt = jmax + 1, jjdiag = qb * 8 + wid;
;     LAS int* flags = (LAS int*)(lds + SCR_OFF) + 516;
; __device__ void phase_attn(const Args& A, LAS unsigned char* lds, int wid_in) {
;     ...
;     if (!g1) for (int u = i0; u < 512; u += st) { const int qb = u >> 5, b = (u & 7) >> 1, h = ((u & 1) << 2) | ((u >> 3) & 3); sb_unit(lds, qkv, attout, b, h, qb, wid, lane); }
.LBB0_301:
	s_and_b64 s[0:1], s[6:7], exec
	s_movk_i32 s101, 0x200
	s_cselect_b32 s101, 0x180, s101
	s_cselect_b32 s0, 0, 0x180
	s_add_i32 s70, s70, s0
	v_readlane_b32 s1, v254, 4
	v_readlane_b32 s0, v254, 7
	s_lshl_b32 s73, s1, 10
	s_and_b32 s71, s0, 0xffffffc0
	s_add_i32 s85, s73, 0
	s_lshl_b32 s0, s1, 2
	s_add_i32 s86, s0, 0
	s_add_i32 s0, s85, 0x14000
	s_lshl_b32 s72, s1, 5
	s_mov_b32 s47, 0
	s_add_i32 s86, s86, 0x20810
	v_writelane_b32 v254, s0, 10
	s_add_i32 s0, s85, 0x16000
	s_add_i32 s89, s1, -4
	s_add_i32 s90, s1, -5
	s_movk_i32 s91, 0x3000
	s_mov_b64 s[48:49], 0x1000
	v_mov_b32_e32 v1, 0
	s_mov_b64 s[50:51], 0x800
	s_add_i32 s92, s85, 0x4000
	s_mov_b64 s[52:53], 0x60800
	s_add_i32 s93, s85, 0x2000
	s_mov_b64 s[54:55], 0x60000
	s_add_i32 s94, s85, 0x6000
	s_add_i32 s95, 0, 0x4000
	s_movk_i32 s96, 0x70
	s_add_i32 s97, s85, 0x10000
	s_add_i32 s84, s85, 0x12000
	s_mov_b32 s82, 0x554ad2e
	s_movk_i32 s83, 0x7fff
	s_mov_b64 s[56:57], 0x5000
	v_mov_b32_e32 v200, 0xc0000
	v_writelane_b32 v254, s0, 11
	s_branch .LBB0_305

; __device__ __forceinline__ bf16_t f2bf(float f) { unsigned u = __float_as_uint(f); u += 0x7FFFu + ((u >> 16) & 1u); return (bf16_t)(u >> 16); }
; __device__ __forceinline__ void sb_unit(LAS unsigned char* lds, const bf16_t* qkv, bf16_t* attout, int b, int h, int qb, int wid, int) {
;     ...
;     asm volatile("" : "+v"(hi), "+v"(r32));
;     bf16_t* op = attout + (size_t)(b * SEQ + q0 + 4 * hi) * DM + h * 128 + r32;
; #pragma unroll
;     for (int r = 0; r < 16; ++r) {
; #pragma unroll
;         for (int d0 = 0; d0 < 4; ++d0) op[d0 * 32] = f2bf(o[d0][r]);
;         op += ((r & 3) == 3 ? 5 : 1) * DM; asm volatile("" : "+v"(op) :: "memory"); }
.LBB0_304:
	s_lshl_b32 s1, s33, 12
	s_add_i32 s43, s43, s1
	s_lshl_b32 s0, s42, 7
	v_lshl_add_u32 v2, v193, 2, s43
	v_ashrrev_i32_e32 v3, 31, v2
	v_lshlrev_b64 v[2:3], 12, v[2:3]
	v_lshl_add_u64 v[2:3], s[44:45], 0, v[2:3]
	s_lshl_b32 s46, s0, 1
	v_lshl_add_u64 v[2:3], v[2:3], 0, s[46:47]
	v_ashrrev_i32_e32 v193, 31, v192
	v_bfe_u32 v0, v112, 16, 1
	v_lshl_add_u64 v[2:3], v[192:193], 1, v[2:3]
	v_add3_u32 v0, v112, v0, s83
	global_store_short_d16_hi v[2:3], v0, off
	v_bfe_u32 v0, v80, 16, 1
	v_add3_u32 v0, v80, v0, s83
	global_store_short_d16_hi v[2:3], v0, off offset:64
	v_bfe_u32 v0, v96, 16, 1
	v_add3_u32 v0, v96, v0, s83
	global_store_short_d16_hi v[2:3], v0, off offset:128
	v_bfe_u32 v0, v128, 16, 1
	v_add3_u32 v0, v128, v0, s83
	global_store_short_d16_hi v[2:3], v0, off offset:192
	v_bfe_u32 v0, v113, 16, 1
	v_lshl_add_u64 v[2:3], v[2:3], 0, s[48:49]
	v_add3_u32 v0, v113, v0, s83
	flat_store_short_d16_hi v[2:3], v0
	v_bfe_u32 v0, v81, 16, 1
	v_add3_u32 v0, v81, v0, s83
	flat_store_short_d16_hi v[2:3], v0 offset:64
	v_bfe_u32 v0, v97, 16, 1
	v_add3_u32 v0, v97, v0, s83
	flat_store_short_d16_hi v[2:3], v0 offset:128
	v_bfe_u32 v0, v129, 16, 1
	v_add3_u32 v0, v129, v0, s83
	flat_store_short_d16_hi v[2:3], v0 offset:192
	v_bfe_u32 v0, v114, 16, 1
	v_lshl_add_u64 v[2:3], v[2:3], 0, s[48:49]
	v_add3_u32 v0, v114, v0, s83
	flat_store_short_d16_hi v[2:3], v0
	v_bfe_u32 v0, v82, 16, 1
	v_add3_u32 v0, v82, v0, s83
	flat_store_short_d16_hi v[2:3], v0 offset:64
	v_bfe_u32 v0, v98, 16, 1
	v_add3_u32 v0, v98, v0, s83
	flat_store_short_d16_hi v[2:3], v0 offset:128
	v_bfe_u32 v0, v130, 16, 1
	v_add3_u32 v0, v130, v0, s83
	flat_store_short_d16_hi v[2:3], v0 offset:192
	v_bfe_u32 v0, v115, 16, 1
	v_lshl_add_u64 v[2:3], v[2:3], 0, s[48:49]
	v_add3_u32 v0, v115, v0, s83
	flat_store_short_d16_hi v[2:3], v0
	v_bfe_u32 v0, v83, 16, 1
	v_add3_u32 v0, v83, v0, s83
	flat_store_short_d16_hi v[2:3], v0 offset:64
	v_bfe_u32 v0, v99, 16, 1
	v_add3_u32 v0, v99, v0, s83
	flat_store_short_d16_hi v[2:3], v0 offset:128
	v_bfe_u32 v0, v131, 16, 1
	v_add3_u32 v0, v131, v0, s83
	flat_store_short_d16_hi v[2:3], v0 offset:192
	v_bfe_u32 v0, v116, 16, 1
	v_lshl_add_u64 v[2:3], v[2:3], 0, s[56:57]
	v_add3_u32 v0, v116, v0, s83
	flat_store_short_d16_hi v[2:3], v0
	v_bfe_u32 v0, v84, 16, 1
	v_add3_u32 v0, v84, v0, s83
	flat_store_short_d16_hi v[2:3], v0 offset:64
	v_bfe_u32 v0, v100, 16, 1
	v_add3_u32 v0, v100, v0, s83
	flat_store_short_d16_hi v[2:3], v0 offset:128
	v_bfe_u32 v0, v132, 16, 1
	v_add3_u32 v0, v132, v0, s83
	flat_store_short_d16_hi v[2:3], v0 offset:192
	v_bfe_u32 v0, v117, 16, 1
	v_lshl_add_u64 v[2:3], v[2:3], 0, s[48:49]
	v_add3_u32 v0, v117, v0, s83
	flat_store_short_d16_hi v[2:3], v0
	v_bfe_u32 v0, v85, 16, 1
	v_add3_u32 v0, v85, v0, s83
	flat_store_short_d16_hi v[2:3], v0 offset:64
	v_bfe_u32 v0, v101, 16, 1
	v_add3_u32 v0, v101, v0, s83
	flat_store_short_d16_hi v[2:3], v0 offset:128
	v_bfe_u32 v0, v133, 16, 1
	v_add3_u32 v0, v133, v0, s83
	flat_store_short_d16_hi v[2:3], v0 offset:192
	v_bfe_u32 v0, v118, 16, 1
	v_lshl_add_u64 v[2:3], v[2:3], 0, s[48:49]
	v_add3_u32 v0, v118, v0, s83
	flat_store_short_d16_hi v[2:3], v0
	v_bfe_u32 v0, v86, 16, 1
	v_add3_u32 v0, v86, v0, s83
	flat_store_short_d16_hi v[2:3], v0 offset:64
	v_bfe_u32 v0, v102, 16, 1
	v_add3_u32 v0, v102, v0, s83
	flat_store_short_d16_hi v[2:3], v0 offset:128
	v_bfe_u32 v0, v134, 16, 1
	v_add3_u32 v0, v134, v0, s83
	flat_store_short_d16_hi v[2:3], v0 offset:192
	v_bfe_u32 v0, v119, 16, 1
	v_lshl_add_u64 v[2:3], v[2:3], 0, s[48:49]
	v_add3_u32 v0, v119, v0, s83
	flat_store_short_d16_hi v[2:3], v0
	v_bfe_u32 v0, v87, 16, 1
	v_add3_u32 v0, v87, v0, s83
	flat_store_short_d16_hi v[2:3], v0 offset:64
	v_bfe_u32 v0, v103, 16, 1
	v_add3_u32 v0, v103, v0, s83
	flat_store_short_d16_hi v[2:3], v0 offset:128
; __device__ __forceinline__ bf16_t f2bf(float f) { unsigned u = __float_as_uint(f); u += 0x7FFFu + ((u >> 16) & 1u); return (bf16_t)(u >> 16); }
; __device__ __forceinline__ void sb_unit(LAS unsigned char* lds, const bf16_t* qkv, bf16_t* attout, int b, int h, int qb, int wid, int) {
;     ...
;     asm volatile("" : "+v"(hi), "+v"(r32));
;     bf16_t* op = attout + (size_t)(b * SEQ + q0 + 4 * hi) * DM + h * 128 + r32;
; #pragma unroll
;     for (int r = 0; r < 16; ++r) {
; #pragma unroll
;         for (int d0 = 0; d0 < 4; ++d0) op[d0 * 32] = f2bf(o[d0][r]);
;         op += ((r & 3) == 3 ? 5 : 1) * DM; asm volatile("" : "+v"(op) :: "memory"); }
; __device__ void phase_attn(const Args& A, LAS unsigned char* lds, int wid_in) {
;     ...
;     if (!g1) for (int u = i0; u < 512; u += st) { const int qb = u >> 5, b = (u & 7) >> 1, h = ((u & 1) << 2) | ((u >> 3) & 3); sb_unit(lds, qkv, attout, b, h, qb, wid, lane); }
	v_bfe_u32 v0, v135, 16, 1
	v_add3_u32 v0, v135, v0, s83
	flat_store_short_d16_hi v[2:3], v0 offset:192
	v_bfe_u32 v0, v120, 16, 1
	v_lshl_add_u64 v[2:3], v[2:3], 0, s[56:57]
	v_add3_u32 v0, v120, v0, s83
	flat_store_short_d16_hi v[2:3], v0
	v_bfe_u32 v0, v88, 16, 1
	v_add3_u32 v0, v88, v0, s83
	flat_store_short_d16_hi v[2:3], v0 offset:64
	v_bfe_u32 v0, v104, 16, 1
	v_add3_u32 v0, v104, v0, s83
	flat_store_short_d16_hi v[2:3], v0 offset:128
	v_bfe_u32 v0, v136, 16, 1
	v_add3_u32 v0, v136, v0, s83
	flat_store_short_d16_hi v[2:3], v0 offset:192
	v_bfe_u32 v0, v121, 16, 1
	v_lshl_add_u64 v[2:3], v[2:3], 0, s[48:49]
	v_add3_u32 v0, v121, v0, s83
	flat_store_short_d16_hi v[2:3], v0
	v_bfe_u32 v0, v89, 16, 1
	v_add3_u32 v0, v89, v0, s83
	flat_store_short_d16_hi v[2:3], v0 offset:64
	v_bfe_u32 v0, v105, 16, 1
	v_add3_u32 v0, v105, v0, s83
	flat_store_short_d16_hi v[2:3], v0 offset:128
	v_bfe_u32 v0, v137, 16, 1
	v_add3_u32 v0, v137, v0, s83
	flat_store_short_d16_hi v[2:3], v0 offset:192
	v_bfe_u32 v0, v122, 16, 1
	v_lshl_add_u64 v[2:3], v[2:3], 0, s[48:49]
	v_add3_u32 v0, v122, v0, s83
	flat_store_short_d16_hi v[2:3], v0
	v_bfe_u32 v0, v90, 16, 1
	v_add3_u32 v0, v90, v0, s83
	flat_store_short_d16_hi v[2:3], v0 offset:64
	v_bfe_u32 v0, v106, 16, 1
	v_add3_u32 v0, v106, v0, s83
	flat_store_short_d16_hi v[2:3], v0 offset:128
	v_bfe_u32 v0, v138, 16, 1
	v_add3_u32 v0, v138, v0, s83
	flat_store_short_d16_hi v[2:3], v0 offset:192
	v_bfe_u32 v0, v123, 16, 1
	v_lshl_add_u64 v[2:3], v[2:3], 0, s[48:49]
	v_add3_u32 v0, v123, v0, s83
	flat_store_short_d16_hi v[2:3], v0
	v_bfe_u32 v0, v91, 16, 1
	v_add3_u32 v0, v91, v0, s83
	flat_store_short_d16_hi v[2:3], v0 offset:64
	v_bfe_u32 v0, v107, 16, 1
	v_add3_u32 v0, v107, v0, s83
	flat_store_short_d16_hi v[2:3], v0 offset:128
	v_bfe_u32 v0, v139, 16, 1
	v_add3_u32 v0, v139, v0, s83
	flat_store_short_d16_hi v[2:3], v0 offset:192
	v_bfe_u32 v0, v124, 16, 1
	v_lshl_add_u64 v[2:3], v[2:3], 0, s[56:57]
	v_add3_u32 v0, v124, v0, s83
	flat_store_short_d16_hi v[2:3], v0
	v_bfe_u32 v0, v92, 16, 1
	v_add3_u32 v0, v92, v0, s83
	flat_store_short_d16_hi v[2:3], v0 offset:64
	v_bfe_u32 v0, v108, 16, 1
	v_add3_u32 v0, v108, v0, s83
	flat_store_short_d16_hi v[2:3], v0 offset:128
	v_bfe_u32 v0, v140, 16, 1
	v_add3_u32 v0, v140, v0, s83
	flat_store_short_d16_hi v[2:3], v0 offset:192
	v_bfe_u32 v0, v125, 16, 1
	v_lshl_add_u64 v[2:3], v[2:3], 0, s[48:49]
	v_add3_u32 v0, v125, v0, s83
	flat_store_short_d16_hi v[2:3], v0
	v_bfe_u32 v0, v93, 16, 1
	v_add3_u32 v0, v93, v0, s83
	flat_store_short_d16_hi v[2:3], v0 offset:64
	v_bfe_u32 v0, v109, 16, 1
	v_add3_u32 v0, v109, v0, s83
	flat_store_short_d16_hi v[2:3], v0 offset:128
	v_bfe_u32 v0, v141, 16, 1
	v_add3_u32 v0, v141, v0, s83
	flat_store_short_d16_hi v[2:3], v0 offset:192
	v_bfe_u32 v0, v126, 16, 1
	v_lshl_add_u64 v[2:3], v[2:3], 0, s[48:49]
	v_add3_u32 v0, v126, v0, s83
	flat_store_short_d16_hi v[2:3], v0
	v_bfe_u32 v0, v94, 16, 1
	v_add3_u32 v0, v94, v0, s83
	flat_store_short_d16_hi v[2:3], v0 offset:64
	v_bfe_u32 v0, v110, 16, 1
	v_add3_u32 v0, v110, v0, s83
	flat_store_short_d16_hi v[2:3], v0 offset:128
	v_bfe_u32 v0, v142, 16, 1
	v_add3_u32 v0, v142, v0, s83
	flat_store_short_d16_hi v[2:3], v0 offset:192
	v_bfe_u32 v0, v127, 16, 1
	v_lshl_add_u64 v[2:3], v[2:3], 0, s[48:49]
	v_add3_u32 v0, v127, v0, s83
	flat_store_short_d16_hi v[2:3], v0
	v_bfe_u32 v0, v95, 16, 1
	v_add3_u32 v0, v95, v0, s83
	flat_store_short_d16_hi v[2:3], v0 offset:64
	v_bfe_u32 v0, v111, 16, 1
	v_add3_u32 v0, v111, v0, s83
	flat_store_short_d16_hi v[2:3], v0 offset:128
	v_bfe_u32 v0, v143, 16, 1
	v_add3_u32 v0, v143, v0, s83
	flat_store_short_d16_hi v[2:3], v0 offset:192
	v_lshl_add_u64 v[2:3], v[2:3], 0, s[56:57]
	s_add_i32 s70, s70, s69
	s_cmp_lt_i32 s70, s101
	s_cbranch_scc0 .LBB0_347

; __global__ void __launch_bounds__(NTHREADS, 2) mega(Args args) {
	.amdhsa_kernel _Z4mega4Args
		.amdhsa_group_segment_fixed_size 0
		.amdhsa_private_segment_fixed_size 0
		.amdhsa_kernarg_size 416
		.amdhsa_user_sgpr_count 2
		.amdhsa_user_sgpr_dispatch_ptr 0
		.amdhsa_user_sgpr_queue_ptr 0
		.amdhsa_user_sgpr_kernarg_segment_ptr 1
		.amdhsa_user_sgpr_dispatch_id 0
		.amdhsa_user_sgpr_kernarg_preload_length 0
		.amdhsa_user_sgpr_kernarg_preload_offset 0
		.amdhsa_user_sgpr_private_segment_size 0
		.amdhsa_uses_dynamic_stack 0
		.amdhsa_enable_private_segment 0
		.amdhsa_system_sgpr_workgroup_id_x 1
		.amdhsa_system_sgpr_workgroup_id_y 0
		.amdhsa_system_sgpr_workgroup_id_z 0
		.amdhsa_system_sgpr_workgroup_info 0
		.amdhsa_system_vgpr_workitem_id 2
		.amdhsa_next_free_vgpr 255
		.amdhsa_next_free_sgpr 102
		.amdhsa_accum_offset 256
		.amdhsa_reserve_vcc 1
		.amdhsa_float_round_mode_32 0
		.amdhsa_float_round_mode_16_64 0
		.amdhsa_float_denorm_mode_32 3
		.amdhsa_float_denorm_mode_16_64 3
		.amdhsa_dx10_clamp 1
		.amdhsa_ieee_mode 1
		.amdhsa_fp16_overflow 0
		.amdhsa_tg_split 0
		.amdhsa_exception_fp_ieee_invalid_op 0
		.amdhsa_exception_fp_denorm_src 0
		.amdhsa_exception_fp_ieee_div_zero 0
		.amdhsa_exception_fp_ieee_overflow 0
		.amdhsa_exception_fp_ieee_underflow 0
		.amdhsa_exception_fp_ieee_inexact 0
		.amdhsa_exception_int_div_zero 0
	.end_amdhsa_kernel
